# v_g34 + MLA loop: next-buffer LDS write addresses precomputed in the hazard gap (distinct registers), tile-end block reduced to waits + ds_writes
# baseline (speedup 1.0000x reference)
; #define MFMA(a, b, c) __builtin_amdgcn_mfma_f32_32x32x16_bf16((a), (b), (c), 0, 0, 0)
; DI unsigned pack2(float a, float b) { f32x2 v = {a, b}; return __builtin_bit_cast(unsigned, __builtin_convertvector(v, bf16v2)); }
; template <int DK, int MODE> ...
;     ...
;           s0[e] = __builtin_amdgcn_exp2f(s0[e] - m); s0[e + 1] = __builtin_amdgcn_exp2f(s0[e + 1] - m); s0[e + 2] = __builtin_amdgcn_exp2f(s0[e + 2] - m); s0[e + 3] = __builtin_amdgcn_exp2f(s0[e + 3] - m);
;           ps0 += s0[e]; ps1 += s0[e + 1]; ps2 += s0[e + 2]; ps3 += s0[e + 3];
;         }
; #pragma unroll
;         for (int e = 0; e < 16; e += 4) {
;           s1[e] = __builtin_amdgcn_exp2f(s1[e] - m); s1[e + 1] = __builtin_amdgcn_exp2f(s1[e + 1] - m); s1[e + 2] = __builtin_amdgcn_exp2f(s1[e + 2] - m); s1[e + 3] = __builtin_amdgcn_exp2f(s1[e + 3] - m);
;           ps0 += s1[e]; ps1 += s1[e + 1]; ps2 += s1[e + 2]; ps3 += s1[e + 3];
;         }
;         lsum += (ps0 + ps1) + (ps2 + ps3);
;     ...
; #pragma unroll
;       for (int j = 0; j < 2; ++j) {
;         u32x4 a, b;
;         a.x = pack2(s0[8 * j], s0[8 * j + 1]); a.y = pack2(s0[8 * j + 2], s0[8 * j + 3]); a.z = pack2(s0[8 * j + 4], s0[8 * j + 5]); a.w = pack2(s0[8 * j + 6], s0[8 * j + 7]);
;         b.x = pack2(s1[8 * j], s1[8 * j + 1]); b.y = pack2(s1[8 * j + 2], s1[8 * j + 3]); b.z = pack2(s1[8 * j + 4], s1[8 * j + 5]); b.w = pack2(s1[8 * j + 6], s1[8 * j + 7]);
;         pf[j] = __builtin_bit_cast(bf16x8, a); pf[2 + j] = __builtin_bit_cast(bf16x8, b);
;       }
;       __builtin_amdgcn_s_setprio(1);
; #pragma unroll
;       for (int j = 0; j < 4; ++j) { o0 = MFMA(vf0[j], pf[j], o0); o1 = MFMA(vf1[j], pf[j], o1); }
;       __builtin_amdgcn_s_setprio(0);
;     }
;     __builtin_amdgcn_sched_barrier(0);
;     if (more) swrite(cur ^ 1);
.LBB0_524:
	v_sub_f32_e32 v0, v64, v155
	v_exp_f32_e32 v14, v0
	v_sub_f32_e32 v0, v65, v155
	v_exp_f32_e32 v64, v0
	v_sub_f32_e32 v0, v66, v155
	v_exp_f32_e32 v15, v0
	v_sub_f32_e32 v0, v67, v155
	v_exp_f32_e32 v65, v0
	v_sub_f32_e32 v0, v68, v155
	v_exp_f32_e32 v66, v0
	v_sub_f32_e32 v0, v69, v155
	v_exp_f32_e32 v68, v0
	v_sub_f32_e32 v0, v70, v155
	v_exp_f32_e32 v67, v0
	v_sub_f32_e32 v0, v71, v155
	v_exp_f32_e32 v69, v0
	v_sub_f32_e32 v0, v72, v155
	v_exp_f32_e32 v70, v0
	v_sub_f32_e32 v0, v73, v155
	v_exp_f32_e32 v72, v0
	v_sub_f32_e32 v0, v74, v155
	v_exp_f32_e32 v71, v0
	v_sub_f32_e32 v0, v75, v155
	v_exp_f32_e32 v73, v0
	v_sub_f32_e32 v0, v76, v155
	v_exp_f32_e32 v74, v0
	v_sub_f32_e32 v0, v77, v155
	v_exp_f32_e32 v76, v0
	v_sub_f32_e32 v0, v78, v155
	v_exp_f32_e32 v75, v0
	v_sub_f32_e32 v0, v79, v155
	v_exp_f32_e32 v77, v0
	v_sub_f32_e32 v0, v48, v155
	v_exp_f32_e32 v78, v0
	v_sub_f32_e32 v0, v49, v155
	v_exp_f32_e32 v176, v0
	v_sub_f32_e32 v0, v50, v155
	v_exp_f32_e32 v79, v0
	v_sub_f32_e32 v0, v51, v155
	v_exp_f32_e32 v177, v0
	v_sub_f32_e32 v0, v52, v155
	v_exp_f32_e32 v178, v0
	v_sub_f32_e32 v0, v53, v155
	v_exp_f32_e32 v180, v0
	v_sub_f32_e32 v0, v54, v155
	v_exp_f32_e32 v179, v0
	v_sub_f32_e32 v0, v55, v155
	v_exp_f32_e32 v181, v0
	v_sub_f32_e32 v0, v56, v155
	v_exp_f32_e32 v182, v0
	v_sub_f32_e32 v0, v57, v155
	v_exp_f32_e32 v184, v0
	v_sub_f32_e32 v0, v58, v155
	v_exp_f32_e32 v183, v0
	v_sub_f32_e32 v0, v59, v155
	v_exp_f32_e32 v185, v0
	v_sub_f32_e32 v0, v60, v155
	v_exp_f32_e32 v186, v0
	v_sub_f32_e32 v0, v61, v155
	v_exp_f32_e32 v200, v0
	v_sub_f32_e32 v0, v62, v155
	v_pk_add_f32 v[48:49], v[66:67], v[14:15]
	v_pk_add_f32 v[50:51], v[68:69], v[64:65]
	v_exp_f32_e32 v187, v0
	v_sub_f32_e32 v0, v63, v155
	v_pk_add_f32 v[48:49], v[70:71], v[48:49]
	v_pk_add_f32 v[50:51], v[72:73], v[50:51]
	v_exp_f32_e32 v201, v0
	v_pk_add_f32 v[202:203], v[74:75], v[48:49]
	v_pk_add_f32 v[204:205], v[76:77], v[50:51]
	v_cvt_pk_bf16_f32 v48, v14, v64
	v_cvt_pk_bf16_f32 v49, v15, v65
	v_pk_add_f32 v[14:15], v[78:79], v[202:203]
	v_pk_add_f32 v[64:65], v[176:177], v[204:205]
	v_pk_add_f32 v[14:15], v[178:179], v[14:15]
	v_pk_add_f32 v[64:65], v[180:181], v[64:65]
	v_pk_add_f32 v[14:15], v[182:183], v[14:15]
	v_pk_add_f32 v[64:65], v[184:185], v[64:65]
	v_pk_add_f32 v[14:15], v[186:187], v[14:15]
	v_pk_add_f32 v[64:65], v[200:201], v[64:65]
	v_cvt_pk_bf16_f32 v50, v66, v68
	v_pk_add_f32 v[14:15], v[14:15], v[64:65]
	v_cvt_pk_bf16_f32 v51, v67, v69
	v_cvt_pk_bf16_f32 v52, v78, v176
	v_cvt_pk_bf16_f32 v53, v79, v177
	v_cvt_pk_bf16_f32 v54, v178, v180
	v_cvt_pk_bf16_f32 v55, v179, v181
	v_cvt_pk_bf16_f32 v56, v70, v72
	v_cvt_pk_bf16_f32 v57, v71, v73
	v_cvt_pk_bf16_f32 v58, v74, v76
	v_cvt_pk_bf16_f32 v59, v75, v77
	v_cvt_pk_bf16_f32 v60, v182, v184
	v_cvt_pk_bf16_f32 v61, v183, v185
	v_cvt_pk_bf16_f32 v62, v186, v200
	v_cvt_pk_bf16_f32 v63, v187, v201
	v_add_f32_e32 v0, v14, v15
	s_setprio 1
	v_mfma_f32_32x32x16_bf16 v[16:31], v[136:139], v[48:51], v[16:31]
	v_add_f32_e32 v151, v151, v0
	v_mfma_f32_32x32x16_bf16 v[32:47], v[140:143], v[48:51], v[32:47]
	v_mfma_f32_32x32x16_bf16 v[16:31], v[108:111], v[56:59], v[16:31]
	v_mfma_f32_32x32x16_bf16 v[32:47], v[132:135], v[56:59], v[32:47]
	v_mfma_f32_32x32x16_bf16 v[16:31], v[100:103], v[52:55], v[16:31]
	v_mfma_f32_32x32x16_bf16 v[32:47], v[104:107], v[52:55], v[32:47]
	v_mfma_f32_32x32x16_bf16 v[16:31], v[96:99], v[60:63], v[16:31]
	v_mfma_f32_32x32x16_bf16 v[32:47], v[92:95], v[60:63], v[32:47]
	s_setprio 0
	s_waitcnt vmcnt(4)
	ds_write_b128 v241, v[88:91]
	s_waitcnt vmcnt(3)
	ds_write_b128 v242, v[84:87]
	s_waitcnt vmcnt(2)
	ds_write_b128 v243, v[10:13]
	s_waitcnt vmcnt(1)
	ds_write_b128 v244, v[6:9] offset:26624
	s_add_i32 s9, s9, 64
	s_add_i32 s10, s10, 1
	s_cmp_eq_u32 s2, s9
	s_waitcnt vmcnt(0)
	ds_write_b128 v245, v[2:5] offset:26624
	s_branch .Lmla_sync

; template <int DK, int MODE> ...
;     ...
;   auto swrite = [&](int buf) {
; #pragma unroll
;     for (int i = 0; i < NKL; ++i) {
;       const int id = tid + 256 * i, row = id / KCH, ch = id % KCH;
;       *(u32x4*)(sK + buf * 64 * LDK + row * LDK + ch * 8) = rk[i];
;     }
; #pragma unroll
;     for (int i = 0; i < 2; ++i) {
;       const int id = tid + 256 * i, row = id >> 3, ch = id & 7;
;       *(u32x4*)(sV + buf * 64 * 72 + row * 72 + ch * 8) = rv[i];
;     }
;     if (MODE == 1) { if (tid < 64) sF[buf * 64 + tid] = Fref - rf; }
;   };
;     ...
;         float mx = s0[0];
; #pragma unroll
;         for (int e = 1; e < 16; ++e) mx = fmaxf(mx, s0[e]);
; #pragma unroll
;         for (int e = 0; e < 16; ++e) mx = fmaxf(mx, s1[e]);
;         mx = fmaxf(mx, __shfl_xor(mx, 32));
;         if (__any(mx > m + 8.f)) {
;           const float mnew = fmaxf(m, mx);
;           const float alpha = __builtin_amdgcn_exp2f(m - mnew);
;           m = mnew; lsum *= alpha;
; #pragma unroll
;           for (int e = 0; e < 16; ++e) { o0[e] *= alpha; o1[e] *= alpha; }
;         }
.LBB0_529:
	v_lshl_add_u64 v[162:163], v[162:163], 0, s[34:35]
	v_lshl_add_u64 v[164:165], v[164:165], 0, s[34:35]
	v_lshl_add_u64 v[166:167], v[166:167], 0, s[36:37]
	v_lshl_add_u64 v[168:169], v[168:169], 0, s[36:37]
	v_lshl_add_u64 v[170:171], v[170:171], 0, s[36:37]
	s_xor_b32 s100, s11, 1
	s_mul_i32 s101, s100, 0x3400
	s_lshl_b32 s100, s100, 12
	s_sub_i32 s100, s101, s100
	v_add_u32_e32 v241, s101, v217
	v_add_u32_e32 v242, s101, v218
	v_add_u32_e32 v243, s101, v219
	v_add_u32_e32 v244, s100, v220
	v_add_u32_e32 v245, s100, v221
	v_max_f32_e32 v0, v64, v65
	v_max3_f32 v0, v0, v66, v67
	v_max3_f32 v0, v0, v68, v69
	v_max3_f32 v0, v0, v70, v71
	v_max3_f32 v0, v0, v72, v73
	v_max3_f32 v0, v0, v74, v75
	v_max3_f32 v0, v0, v76, v77
	v_max3_f32 v0, v0, v78, v79
	v_max3_f32 v0, v0, v48, v49
	v_max3_f32 v0, v0, v50, v51
	v_max3_f32 v0, v0, v52, v53
	v_max3_f32 v0, v0, v54, v55
	v_max3_f32 v0, v0, v56, v57
	v_max3_f32 v0, v0, v58, v59
	v_max3_f32 v0, v0, v60, v61
	v_max3_f32 v0, v0, v62, v63
	ds_bpermute_b32 v14, v216, v0
	s_waitcnt lgkmcnt(0)
	v_max_f32_e32 v0, v0, v14
	v_add_f32_e32 v14, 0x41000000, v155
	v_cmp_gt_f32_e32 vcc, v0, v14
	s_cbranch_vccz .LBB0_524
	v_max_f32_e32 v0, v0, v0
	v_max_f32_e32 v14, v155, v155
	v_max_f32_e32 v14, v14, v0
	v_sub_f32_e32 v0, v155, v14
	v_exp_f32_e32 v0, v0
	v_mov_b32_e32 v155, v14
	v_pk_mul_f32 v[30:31], v[30:31], v[0:1] op_sel_hi:[1,0]
	v_pk_mul_f32 v[28:29], v[28:29], v[0:1] op_sel_hi:[1,0]
	v_pk_mul_f32 v[26:27], v[26:27], v[0:1] op_sel_hi:[1,0]
	v_pk_mul_f32 v[24:25], v[24:25], v[0:1] op_sel_hi:[1,0]
	v_pk_mul_f32 v[22:23], v[22:23], v[0:1] op_sel_hi:[1,0]
	v_pk_mul_f32 v[20:21], v[20:21], v[0:1] op_sel_hi:[1,0]
	v_pk_mul_f32 v[18:19], v[18:19], v[0:1] op_sel_hi:[1,0]
	v_pk_mul_f32 v[16:17], v[16:17], v[0:1] op_sel_hi:[1,0]
	v_pk_mul_f32 v[46:47], v[46:47], v[0:1] op_sel_hi:[1,0]
	v_pk_mul_f32 v[44:45], v[44:45], v[0:1] op_sel_hi:[1,0]
	v_pk_mul_f32 v[42:43], v[42:43], v[0:1] op_sel_hi:[1,0]
	v_pk_mul_f32 v[40:41], v[40:41], v[0:1] op_sel_hi:[1,0]
	v_pk_mul_f32 v[38:39], v[38:39], v[0:1] op_sel_hi:[1,0]
	v_pk_mul_f32 v[36:37], v[36:37], v[0:1] op_sel_hi:[1,0]
	v_pk_mul_f32 v[34:35], v[34:35], v[0:1] op_sel_hi:[1,0]
	v_pk_mul_f32 v[32:33], v[32:33], v[0:1] op_sel_hi:[1,0]
	v_mul_f32_e32 v151, v151, v0
	s_branch .LBB0_524
